# adaLN GEMV fully pipelined: first item's weight loads issued behind the silu(c) staging loads, later items' loads issued before the previous item's reduction; pool prologue wait and attention prologue
# baseline (speedup 1.0000x reference)
.LBB0_25:
.Lada_part_b:
	v_or_b32_e32 v0, 6, v13
	v_lshl_add_u32 v89, v13, 2, 0
	v_mad_i64_i32 v[0:1], s[0:1], v0, s3, v[6:7]
	ds_read_b128 v[38:41], v89
	ds_read_b128 v[42:45], v89 offset:16
	global_load_dwordx4 v[46:49], v[0:1], off nt
	v_or_b32_e32 v2, 7, v13
	v_or_b32_e32 v3, 8, v13
	v_or_b32_e32 v74, 9, v13
	ds_read_b128 v[50:53], v89 offset:8192
	ds_read_b128 v[54:57], v89 offset:8208
	ds_read_b128 v[58:61], v89 offset:16384
	ds_read_b128 v[62:65], v89 offset:16400
	ds_read_b128 v[66:69], v89 offset:24576
	ds_read_b128 v[70:73], v89 offset:24592
	v_mad_i64_i32 v[82:83], s[0:1], v2, s3, v[6:7]
	v_mad_i64_i32 v[84:85], s[0:1], v3, s3, v[6:7]
	v_mad_i64_i32 v[86:87], s[0:1], v74, s3, v[6:7]
	global_load_dwordx4 v[74:77], v[82:83], off nt
	global_load_dwordx4 v[78:81], v[84:85], off nt
	global_load_dwordx4 v[0:3], v[86:87], off nt
	s_waitcnt lgkmcnt(7)
	v_mov_b32_e32 v88, v41
	s_waitcnt lgkmcnt(5)
	v_mov_b32_e32 v90, v53
	s_waitcnt lgkmcnt(3)
	v_mov_b32_e32 v92, v61
	s_waitcnt lgkmcnt(1)
	v_mov_b32_e32 v94, v69
	s_waitcnt vmcnt(9)
	v_pk_fma_f32 v[82:83], v[16:17], v[38:39], 0 op_sel_hi:[1,0,0]
	v_pk_fma_f32 v[84:85], v[14:15], v[38:39], 0 op_sel_hi:[1,0,0]
	v_pk_fma_f32 v[86:87], v[16:17], v[50:51], 0 op_sel_hi:[1,0,0]
	v_pk_fma_f32 v[96:97], v[14:15], v[50:51], 0 op_sel_hi:[1,0,0]
	v_pk_fma_f32 v[98:99], v[16:17], v[58:59], 0 op_sel_hi:[1,0,0]
	v_pk_fma_f32 v[100:101], v[14:15], v[58:59], 0 op_sel_hi:[1,0,0]
	v_pk_fma_f32 v[14:15], v[14:15], v[66:67], 0 op_sel_hi:[1,0,0]
	v_pk_fma_f32 v[16:17], v[16:17], v[66:67], 0 op_sel_hi:[1,0,0]
	s_waitcnt vmcnt(8)
	v_pk_fma_f32 v[82:83], v[20:21], v[38:39], v[82:83] op_sel:[0,1,0]
	v_pk_fma_f32 v[38:39], v[18:19], v[38:39], v[84:85] op_sel:[0,1,0]
	v_pk_fma_f32 v[84:85], v[20:21], v[50:51], v[86:87] op_sel:[0,1,0]
	v_pk_fma_f32 v[50:51], v[18:19], v[50:51], v[96:97] op_sel:[0,1,0]
	v_pk_fma_f32 v[86:87], v[20:21], v[58:59], v[98:99] op_sel:[0,1,0]
	v_pk_fma_f32 v[58:59], v[18:19], v[58:59], v[100:101] op_sel:[0,1,0]
	v_pk_fma_f32 v[14:15], v[18:19], v[66:67], v[14:15] op_sel:[0,1,0]
	v_pk_fma_f32 v[16:17], v[20:21], v[66:67], v[16:17] op_sel:[0,1,0]
	s_waitcnt vmcnt(7)
	v_pk_fma_f32 v[18:19], v[24:25], v[40:41], v[82:83] op_sel_hi:[1,0,1]
	v_pk_fma_f32 v[20:21], v[22:23], v[40:41], v[38:39] op_sel_hi:[1,0,1]
	v_pk_fma_f32 v[38:39], v[24:25], v[52:53], v[84:85] op_sel_hi:[1,0,1]
	v_pk_fma_f32 v[40:41], v[22:23], v[52:53], v[50:51] op_sel_hi:[1,0,1]
	v_pk_fma_f32 v[52:53], v[22:23], v[60:61], v[58:59] op_sel_hi:[1,0,1]
	v_pk_fma_f32 v[14:15], v[22:23], v[68:69], v[14:15] op_sel_hi:[1,0,1]
	v_pk_fma_f32 v[50:51], v[24:25], v[60:61], v[86:87] op_sel_hi:[1,0,1]
	v_pk_fma_f32 v[16:17], v[24:25], v[68:69], v[16:17] op_sel_hi:[1,0,1]
	s_waitcnt vmcnt(6)
	v_pk_fma_f32 v[18:19], v[28:29], v[88:89], v[18:19] op_sel_hi:[1,0,1]
	v_pk_fma_f32 v[20:21], v[26:27], v[88:89], v[20:21] op_sel_hi:[1,0,1]
	v_pk_fma_f32 v[22:23], v[28:29], v[90:91], v[38:39] op_sel_hi:[1,0,1]
	v_pk_fma_f32 v[24:25], v[26:27], v[90:91], v[40:41] op_sel_hi:[1,0,1]
	v_pk_fma_f32 v[40:41], v[26:27], v[92:93], v[52:53] op_sel_hi:[1,0,1]
	v_pk_fma_f32 v[26:27], v[26:27], v[94:95], v[14:15] op_sel_hi:[1,0,1]
	v_or_b32_e32 v14, 10, v13
	v_pk_fma_f32 v[38:39], v[28:29], v[92:93], v[50:51] op_sel_hi:[1,0,1]
	v_pk_fma_f32 v[28:29], v[28:29], v[94:95], v[16:17] op_sel_hi:[1,0,1]
	s_waitcnt vmcnt(5)
	v_pk_fma_f32 v[50:51], v[32:33], v[42:43], v[18:19] op_sel_hi:[1,0,1]
	v_mad_i64_i32 v[14:15], s[0:1], v14, s3, v[6:7]
	v_pk_fma_f32 v[52:53], v[30:31], v[42:43], v[20:21] op_sel_hi:[1,0,1]
	v_pk_fma_f32 v[22:23], v[32:33], v[54:55], v[22:23] op_sel_hi:[1,0,1]
	v_or_b32_e32 v18, 11, v13
	global_load_dwordx4 v[14:17], v[14:15], off nt
	v_pk_fma_f32 v[24:25], v[30:31], v[54:55], v[24:25] op_sel_hi:[1,0,1]
	v_pk_fma_f32 v[38:39], v[32:33], v[62:63], v[38:39] op_sel_hi:[1,0,1]
	v_pk_fma_f32 v[40:41], v[30:31], v[62:63], v[40:41] op_sel_hi:[1,0,1]
	v_mad_i64_i32 v[18:19], s[0:1], v18, s3, v[6:7]
	s_waitcnt lgkmcnt(0)
	v_pk_fma_f32 v[28:29], v[32:33], v[70:71], v[28:29] op_sel_hi:[1,0,1]
	v_pk_fma_f32 v[26:27], v[30:31], v[70:71], v[26:27] op_sel_hi:[1,0,1]
	s_waitcnt vmcnt(5)
	v_pk_fma_f32 v[30:31], v[36:37], v[42:43], v[50:51] op_sel:[0,1,0]
	v_pk_fma_f32 v[32:33], v[34:35], v[42:43], v[52:53] op_sel:[0,1,0]
	v_pk_fma_f32 v[42:43], v[36:37], v[54:55], v[22:23] op_sel:[0,1,0]
	v_or_b32_e32 v22, 12, v13
	global_load_dwordx4 v[18:21], v[18:19], off nt
	v_pk_fma_f32 v[50:51], v[34:35], v[54:55], v[24:25] op_sel:[0,1,0]
	v_mad_i64_i32 v[22:23], s[0:1], v22, s3, v[6:7]
	v_pk_fma_f32 v[40:41], v[34:35], v[62:63], v[40:41] op_sel:[0,1,0]
	v_pk_fma_f32 v[34:35], v[34:35], v[70:71], v[26:27] op_sel:[0,1,0]
	v_or_b32_e32 v26, 13, v13
	global_load_dwordx4 v[22:25], v[22:23], off nt
	s_waitcnt vmcnt(6)
	v_pk_fma_f32 v[52:53], v[48:49], v[44:45], v[30:31] op_sel_hi:[1,0,1]
	v_mad_i64_i32 v[26:27], s[0:1], v26, s3, v[6:7]
	v_or_b32_e32 v30, 14, v13
	v_pk_fma_f32 v[38:39], v[36:37], v[62:63], v[38:39] op_sel:[0,1,0]
	v_pk_fma_f32 v[36:37], v[36:37], v[70:71], v[28:29] op_sel:[0,1,0]
	global_load_dwordx4 v[26:29], v[26:27], off nt
	v_mad_i64_i32 v[30:31], s[0:1], v30, s3, v[6:7]
	v_or_b32_e32 v13, 15, v13
	v_pk_fma_f32 v[54:55], v[46:47], v[44:45], v[32:33] op_sel_hi:[1,0,1]
	global_load_dwordx4 v[30:33], v[30:31], off nt
	v_mad_i64_i32 v[6:7], s[0:1], v13, s3, v[6:7]
	v_pk_fma_f32 v[42:43], v[48:49], v[56:57], v[42:43] op_sel_hi:[1,0,1]
	v_pk_fma_f32 v[50:51], v[46:47], v[56:57], v[50:51] op_sel_hi:[1,0,1]
	v_pk_fma_f32 v[58:59], v[48:49], v[64:65], v[38:39] op_sel_hi:[1,0,1]
	v_pk_fma_f32 v[60:61], v[46:47], v[64:65], v[40:41] op_sel_hi:[1,0,1]
	v_pk_fma_f32 v[62:63], v[48:49], v[72:73], v[36:37] op_sel_hi:[1,0,1]
	v_pk_fma_f32 v[66:67], v[46:47], v[72:73], v[34:35] op_sel_hi:[1,0,1]
	ds_read_b128 v[34:37], v89 offset:32
	ds_read_b128 v[38:41], v89 offset:48
	global_load_dwordx4 v[46:49], v[6:7], off nt
	v_mov_b32_e32 v44, v57
	s_waitcnt vmcnt(8)
	v_pk_fma_f32 v[68:69], v[76:77], v[44:45], v[42:43] op_sel_hi:[1,0,1]
	v_mov_b32_e32 v42, v65
	v_mov_b32_e32 v6, v45
	v_pk_fma_f32 v[82:83], v[76:77], v[42:43], v[58:59] op_sel_hi:[1,0,1]
	v_pk_fma_f32 v[84:85], v[74:75], v[42:43], v[60:61] op_sel_hi:[1,0,1]
	v_mov_b32_e32 v42, v73
	v_pk_fma_f32 v[52:53], v[76:77], v[6:7], v[52:53] op_sel_hi:[1,0,1]
	v_pk_fma_f32 v[6:7], v[74:75], v[6:7], v[54:55] op_sel_hi:[1,0,1]
	v_pk_fma_f32 v[70:71], v[74:75], v[44:45], v[50:51] op_sel_hi:[1,0,1]
	v_pk_fma_f32 v[72:73], v[76:77], v[42:43], v[62:63] op_sel_hi:[1,0,1]
	v_pk_fma_f32 v[74:75], v[74:75], v[42:43], v[66:67] op_sel_hi:[1,0,1]
	ds_read_b128 v[42:45], v89 offset:8224
	s_waitcnt vmcnt(7) lgkmcnt(2)
	v_pk_fma_f32 v[76:77], v[80:81], v[34:35], v[52:53] op_sel_hi:[1,0,1]
	ds_read_b128 v[50:53], v89 offset:16416
	ds_read_b128 v[54:57], v89 offset:8240
	ds_read_b128 v[58:61], v89 offset:24608
	ds_read_b128 v[62:65], v89 offset:16432
	v_pk_fma_f32 v[6:7], v[78:79], v[34:35], v[6:7] op_sel_hi:[1,0,1]
	s_waitcnt lgkmcnt(4)
	v_pk_fma_f32 v[86:87], v[80:81], v[42:43], v[68:69] op_sel_hi:[1,0,1]
	ds_read_b128 v[66:69], v89 offset:24624
	v_pk_fma_f32 v[70:71], v[78:79], v[42:43], v[70:71] op_sel_hi:[1,0,1]
	s_waitcnt lgkmcnt(4)
	v_pk_fma_f32 v[82:83], v[80:81], v[50:51], v[82:83] op_sel_hi:[1,0,1]
	v_pk_fma_f32 v[84:85], v[78:79], v[50:51], v[84:85] op_sel_hi:[1,0,1]
	s_waitcnt lgkmcnt(2)
	v_pk_fma_f32 v[74:75], v[78:79], v[58:59], v[74:75] op_sel_hi:[1,0,1]
	v_pk_fma_f32 v[72:73], v[80:81], v[58:59], v[72:73] op_sel_hi:[1,0,1]
	s_waitcnt vmcnt(6)
	v_pk_fma_f32 v[76:77], v[2:3], v[34:35], v[76:77] op_sel:[0,1,0]
	v_pk_fma_f32 v[6:7], v[0:1], v[34:35], v[6:7] op_sel:[0,1,0]
	v_pk_fma_f32 v[34:35], v[2:3], v[42:43], v[86:87] op_sel:[0,1,0]
	v_pk_fma_f32 v[42:43], v[0:1], v[42:43], v[70:71] op_sel:[0,1,0]
	v_pk_fma_f32 v[70:71], v[2:3], v[50:51], v[82:83] op_sel:[0,1,0]
	v_pk_fma_f32 v[50:51], v[0:1], v[50:51], v[84:85] op_sel:[0,1,0]
	v_pk_fma_f32 v[0:1], v[0:1], v[58:59], v[74:75] op_sel:[0,1,0]
	v_pk_fma_f32 v[2:3], v[2:3], v[58:59], v[72:73] op_sel:[0,1,0]
	s_waitcnt vmcnt(5)
	v_pk_fma_f32 v[58:59], v[16:17], v[36:37], v[76:77] op_sel_hi:[1,0,1]
	v_pk_fma_f32 v[6:7], v[14:15], v[36:37], v[6:7] op_sel_hi:[1,0,1]
	v_pk_fma_f32 v[34:35], v[16:17], v[44:45], v[34:35] op_sel_hi:[1,0,1]
	v_pk_fma_f32 v[42:43], v[14:15], v[44:45], v[42:43] op_sel_hi:[1,0,1]
	v_pk_fma_f32 v[50:51], v[14:15], v[52:53], v[50:51] op_sel_hi:[1,0,1]
	v_pk_fma_f32 v[0:1], v[14:15], v[60:61], v[0:1] op_sel_hi:[1,0,1]
	v_mov_b32_e32 v14, v37
	v_mov_b32_e32 v44, v61
	v_pk_fma_f32 v[70:71], v[16:17], v[52:53], v[70:71] op_sel_hi:[1,0,1]
	v_pk_fma_f32 v[2:3], v[16:17], v[60:61], v[2:3] op_sel_hi:[1,0,1]
	v_mov_b32_e32 v36, v53
	s_waitcnt vmcnt(4)
	v_pk_fma_f32 v[16:17], v[20:21], v[14:15], v[58:59] op_sel_hi:[1,0,1]
	v_pk_fma_f32 v[6:7], v[18:19], v[14:15], v[6:7] op_sel_hi:[1,0,1]
	v_mov_b32_e32 v14, v45
	v_pk_fma_f32 v[0:1], v[18:19], v[44:45], v[0:1] op_sel_hi:[1,0,1]
	v_pk_fma_f32 v[34:35], v[20:21], v[14:15], v[34:35] op_sel_hi:[1,0,1]
	v_pk_fma_f32 v[14:15], v[18:19], v[14:15], v[42:43] op_sel_hi:[1,0,1]
	v_pk_fma_f32 v[42:43], v[20:21], v[36:37], v[70:71] op_sel_hi:[1,0,1]
	v_pk_fma_f32 v[36:37], v[18:19], v[36:37], v[50:51] op_sel_hi:[1,0,1]
	v_pk_fma_f32 v[2:3], v[20:21], v[44:45], v[2:3] op_sel_hi:[1,0,1]
	s_waitcnt vmcnt(3)
	v_pk_fma_f32 v[16:17], v[24:25], v[38:39], v[16:17] op_sel_hi:[1,0,1]
	v_pk_fma_f32 v[6:7], v[22:23], v[38:39], v[6:7] op_sel_hi:[1,0,1]
	s_waitcnt lgkmcnt(0)
	v_pk_fma_f32 v[0:1], v[22:23], v[66:67], v[0:1] op_sel_hi:[1,0,1]
	v_pk_fma_f32 v[18:19], v[24:25], v[54:55], v[34:35] op_sel_hi:[1,0,1]
	v_pk_fma_f32 v[14:15], v[22:23], v[54:55], v[14:15] op_sel_hi:[1,0,1]
	v_pk_fma_f32 v[34:35], v[22:23], v[62:63], v[36:37] op_sel_hi:[1,0,1]
	v_pk_fma_f32 v[2:3], v[24:25], v[66:67], v[2:3] op_sel_hi:[1,0,1]
	s_waitcnt vmcnt(2)
	v_pk_fma_f32 v[16:17], v[28:29], v[38:39], v[16:17] op_sel:[0,1,0]
	v_pk_fma_f32 v[6:7], v[26:27], v[38:39], v[6:7] op_sel:[0,1,0]
	v_pk_fma_f32 v[0:1], v[26:27], v[66:67], v[0:1] op_sel:[0,1,0]
	v_pk_fma_f32 v[20:21], v[24:25], v[62:63], v[42:43] op_sel_hi:[1,0,1]
	v_pk_fma_f32 v[18:19], v[28:29], v[54:55], v[18:19] op_sel:[0,1,0]
	v_pk_fma_f32 v[14:15], v[26:27], v[54:55], v[14:15] op_sel:[0,1,0]
	v_pk_fma_f32 v[22:23], v[26:27], v[62:63], v[34:35] op_sel:[0,1,0]
	v_pk_fma_f32 v[2:3], v[28:29], v[66:67], v[2:3] op_sel:[0,1,0]
	s_waitcnt vmcnt(1)
	v_pk_fma_f32 v[16:17], v[32:33], v[40:41], v[16:17] op_sel_hi:[1,0,1]
	v_pk_fma_f32 v[6:7], v[30:31], v[40:41], v[6:7] op_sel_hi:[1,0,1]
	v_pk_fma_f32 v[26:27], v[30:31], v[68:69], v[0:1] op_sel_hi:[1,0,1]
	v_mov_b32_e32 v0, v41
	v_pk_fma_f32 v[20:21], v[28:29], v[62:63], v[20:21] op_sel:[0,1,0]
	v_pk_fma_f32 v[18:19], v[32:33], v[56:57], v[18:19] op_sel_hi:[1,0,1]
	v_pk_fma_f32 v[14:15], v[30:31], v[56:57], v[14:15] op_sel_hi:[1,0,1]
	v_pk_fma_f32 v[24:25], v[32:33], v[68:69], v[2:3] op_sel_hi:[1,0,1]
	s_waitcnt vmcnt(0)
	v_pk_fma_f32 v[2:3], v[48:49], v[0:1], v[16:17] op_sel_hi:[1,0,1]
	v_pk_fma_f32 v[0:1], v[46:47], v[0:1], v[6:7] op_sel_hi:[1,0,1]
	v_mov_b32_e32 v6, v57
	v_pk_fma_f32 v[20:21], v[32:33], v[64:65], v[20:21] op_sel_hi:[1,0,1]
	v_pk_fma_f32 v[22:23], v[30:31], v[64:65], v[22:23] op_sel_hi:[1,0,1]
	v_pk_fma_f32 v[16:17], v[48:49], v[6:7], v[18:19] op_sel_hi:[1,0,1]
	v_pk_fma_f32 v[14:15], v[46:47], v[6:7], v[14:15] op_sel_hi:[1,0,1]
	v_mov_b32_e32 v6, v65
	v_pk_fma_f32 v[20:21], v[48:49], v[6:7], v[20:21] op_sel_hi:[1,0,1]
	v_pk_fma_f32 v[18:19], v[46:47], v[6:7], v[22:23] op_sel_hi:[1,0,1]
	v_mov_b32_e32 v6, v69
	v_pk_fma_f32 v[24:25], v[48:49], v[6:7], v[24:25] op_sel_hi:[1,0,1]
	v_pk_fma_f32 v[22:23], v[46:47], v[6:7], v[26:27] op_sel_hi:[1,0,1]
	ds_write_b128 v12, v[0:3] offset:32768
	ds_write_b128 v12, v[14:17] offset:33024
	ds_write_b128 v12, v[18:21] offset:33280
	ds_write_b128 v12, v[22:25] offset:33536
	s_add_i32 s100, s8, s34
	s_cmpk_lt_i32 s100, 0x300
	s_cbranch_scc0 .Lada_nopf
	s_mul_hi_i32 s0, s100, 0x2aaaaaab
	s_lshr_b32 s1, s0, 31
	s_ashr_i32 s99, s0, 5
	s_add_i32 s99, s99, s1
	s_mul_i32 s0, s99, 0xc0
	s_sub_i32 s0, s100, s0
	s_lshl_b32 s98, s0, 6
	v_or_b32_e32 v148, s98, v8
	v_ashrrev_i32_e32 v149, 31, v148
	v_lshl_add_u32 v13, s99, 9, v9
	v_lshl_add_u64 v[6:7], v[148:149], 2, s[22:23]
	v_mad_i64_i32 v[148:149], s[0:1], v13, s3, v[6:7]
	global_load_dwordx4 v[14:17], v[148:149], off nt
	v_or_b32_e32 v148, 1, v13
	v_mad_i64_i32 v[148:149], s[0:1], v148, s3, v[6:7]
	global_load_dwordx4 v[18:21], v[148:149], off nt
	v_or_b32_e32 v148, 2, v13
	v_mad_i64_i32 v[148:149], s[0:1], v148, s3, v[6:7]
	global_load_dwordx4 v[22:25], v[148:149], off nt
	v_or_b32_e32 v148, 3, v13
	v_mad_i64_i32 v[148:149], s[0:1], v148, s3, v[6:7]
	global_load_dwordx4 v[26:29], v[148:149], off nt
	v_or_b32_e32 v148, 4, v13
	v_mad_i64_i32 v[148:149], s[0:1], v148, s3, v[6:7]
	global_load_dwordx4 v[30:33], v[148:149], off nt
	v_or_b32_e32 v148, 5, v13
	v_mad_i64_i32 v[148:149], s[0:1], v148, s3, v[6:7]
	global_load_dwordx4 v[34:37], v[148:149], off nt
